# FoX layer: V^T also written as MFMA fragment images by the swapped V GEMM epilogue (every FoX LDS-DMA piece 1 KiB contiguous)
# speedup vs baseline: 1.0155x; 1.0033x over previous
.LBB0_163:
	s_lshl_b32 s4, s71, 2
	s_add_i32 s40, s4, 0
	s_cmp_gt_i32 s71, 0
	s_cselect_b64 s[28:29], -1, 0
	s_lshl_b32 s6, s71, 5
	s_cmp_lt_i32 s71, 4
	v_lshrrev_b32_e32 v2, 5, v243
	s_cselect_b64 s[4:5], -1, 0
	s_cmp_gt_i32 s71, 3
	v_lshlrev_b32_e32 v166, 3, v2
	v_lshlrev_b32_e32 v2, 4, v2
	v_mov_b32_e32 v3, v0
	s_cselect_b64 s[30:31], -1, 0
	s_lshl_b32 s34, s71, 4
	v_lshlrev_b32_e32 v4, 4, v243
	v_mov_b32_e32 v5, v0
	v_lshl_add_u64 v[168:169], s[96:97], 0, v[4:5]
	v_lshl_add_u64 v[2:3], s[82:83], 0, v[2:3]
	s_add_i32 s7, s34, 0x7fffffc0
	s_and_b32 s78, s6, 32
	v_and_b32_e32 v4, 31, v242
	s_and_b32 s7, s7, 0x7fffffe0
	v_lshl_add_u64 v[170:171], v[2:3], 0, s[78:79]
	v_lshrrev_b32_e32 v2, 1, v242
	v_lshlrev_b32_e32 v3, 1, v243
	v_or_b32_e32 v186, s6, v4
	v_or_b32_e32 v187, s7, v4
	v_and_b32_e32 v2, 4, v2
	v_and_b32_e32 v3, 8, v3
	v_and_b32_e32 v4, 19, v242
	v_and_b32_e32 v1, 64, v238
	v_or3_b32 v188, v2, v4, v3
	v_add_u32_e32 v2, -1, v238
	v_cmp_lt_i32_e32 vcc, v2, v1
	v_mov_b32_e32 v167, v0
	v_lshl_add_u64 v[172:173], s[18:19], 0, v[166:167]
	v_cndmask_b32_e32 v2, v2, v238, vcc
	v_lshlrev_b32_e32 v167, 2, v2
	v_add_u32_e32 v2, -2, v238
	v_cmp_lt_i32_e32 vcc, v2, v1
	s_ashr_i32 s35, s34, 31
	s_and_b64 s[36:37], s[4:5], exec
	v_cndmask_b32_e32 v2, v2, v238, vcc
	v_lshlrev_b32_e32 v190, 2, v2
	v_add_u32_e32 v2, -4, v238
	v_cmp_lt_i32_e32 vcc, v2, v1
	s_mov_b32 s36, 0x800
	v_readlane_b32 s37, v255, 5
	v_cndmask_b32_e32 v2, v2, v238, vcc
	v_lshlrev_b32_e32 v191, 2, v2
	v_add_u32_e32 v2, -8, v238
	v_cmp_lt_i32_e32 vcc, v2, v1
	v_lshlrev_b32_e32 v184, 3, v242
	v_cmp_eq_u32_e64 s[2:3], 63, v243
	v_cndmask_b32_e32 v2, v2, v238, vcc
	v_lshlrev_b32_e32 v192, 2, v2
	v_add_u32_e32 v2, -16, v238
	v_cmp_lt_i32_e32 vcc, v2, v1
	v_lshl_add_u32 v185, v242, 5, 0
	v_lshl_add_u32 v189, v243, 4, 0
	v_cndmask_b32_e32 v2, v2, v238, vcc
	v_lshlrev_b32_e32 v193, 2, v2
	v_subrev_u32_e32 v2, 32, v238
	v_cmp_lt_i32_e32 vcc, v2, v1
	v_add_u32_e32 v1, 64, v1
	v_cmp_eq_u32_e64 s[6:7], 0, v243
	v_cndmask_b32_e32 v2, v2, v238, vcc
	v_lshlrev_b32_e32 v202, 2, v2
	v_xor_b32_e32 v2, 32, v238
	v_cmp_lt_i32_e32 vcc, v2, v1
	v_cmp_gt_u32_e64 s[8:9], 2, v243
	v_cmp_gt_u32_e64 s[10:11], 4, v243
	v_cndmask_b32_e32 v1, v238, v2, vcc
	v_lshlrev_b32_e32 v203, 2, v1
	v_and_b32_e32 v1, 32, v243
	v_cmp_gt_u32_e64 s[12:13], 8, v243
	v_cmp_gt_u32_e64 s[14:15], 16, v243
	v_cmp_gt_u32_e64 s[16:17], 32, v243
	s_mov_b32 s41, 6
	v_add_u32_e32 v204, s37, v1
	v_lshlrev_b32_e32 v174, 1, v166
	s_lshl_b32 s36, s36, 1
	s_branch .LBB0_165

.LBB0_170:
	v_pk_add_f32 v[6:7], v[10:11], v[6:7] op_sel_hi:[0,1]
	v_pk_add_f32 v[8:9], v[10:11], v[8:9] op_sel_hi:[0,1]
	v_xor_b32_e32 v7, 0x80000000, v7
	v_xor_b32_e32 v6, 0x80000000, v6
	v_xor_b32_e32 v9, 0x80000000, v9
	v_xor_b32_e32 v8, 0x80000000, v8
	v_pk_add_f32 v[4:5], v[10:11], v[4:5] op_sel_hi:[0,1]
	v_pk_add_f32 v[2:3], v[10:11], v[2:3] op_sel_hi:[0,1]
	ds_write_b128 v185, v[6:9]
	v_xor_b32_e32 v5, 0x80000000, v5
	v_xor_b32_e32 v4, 0x80000000, v4
	v_xor_b32_e32 v7, 0x80000000, v3
	v_xor_b32_e32 v6, 0x80000000, v2
	ds_write_b128 v185, v[4:7] offset:16
	s_lshl_b32 s98, s43, 4
	s_add_i32 s98, s98, s44
	s_lshl_b32 s98, s98, 19
	s_mov_b32 s99, 0
	s_lshl_b32 s100, s71, 10
	s_add_i32 s100, s100, s98
	s_or_b32 s100, s100, 0x4000000
	s_mov_b32 s101, 0
	v_lshlrev_b32_e32 v4, 4, v243
	v_mov_b32_e32 v5, v0
	s_lshl_b32 s38, s44, 6
	s_lshl_b32 s39, s43, 10
	s_lshl_b32 s78, s44, 7
	s_or_b32 s38, s38, s39
	v_lshl_add_u64 v[2:3], s[82:83], 0, v[4:5]
	v_lshl_add_u64 v[4:5], s[96:97], 0, v[4:5]
	v_lshl_add_u64 v[4:5], v[4:5], 0, s[100:101]
	s_and_b32 s100, s100, 0x3ffffff
	s_andn2_b32 s100, s100, 0x1000
	v_mov_b32_e32 v175, v0
	s_nop 0
	v_lshl_add_u64 v[2:3], v[2:3], 0, s[100:101]
	s_and_b32 s42, s33, 1
	v_add_u32_e32 v205, s37, v186
	v_lshl_add_u64 v[176:177], v[168:169], 0, s[98:99]
	v_lshl_add_u64 v[178:179], v[172:173], 0, s[78:79]
	v_cndmask_b32_e64 v181, v3, v5, s[4:5]
	v_cndmask_b32_e64 v180, v2, v4, s[4:5]
	s_mov_b32 s43, 0
	s_waitcnt lgkmcnt(0)
	s_barrier
	s_branch .LBB0_172

.LBB0_294:
	s_lshr_b32 s98, s40, 4
	s_lshl_b32 s98, s98, 4
	s_lshl_b32 s99, s41, 2
	s_add_i32 s98, s98, s99
	s_lshr_b32 s99, s71, 2
	s_add_i32 s98, s98, s99
	s_lshl_b32 s98, s98, 19
	s_and_b32 s99, s40, 15
	s_lshl_b32 s99, s99, 15
	s_add_i32 s98, s98, s99
	s_add_u32 s98, s82, s98
	s_addc_u32 s99, s83, 0
	s_mov_b32 s100, 0x4000
	s_mov_b32 s101, 0
	s_lshl_b32 s16, s40, 8
	v_or_b32_e32 v134, s16, v155
	v_or_b32_e32 v134, v1, v134
	v_ashrrev_i32_e32 v135, 31, v134
	v_lshlrev_b64 v[134:135], 6, v[134:135]
	v_lshl_add_u64 v[152:153], s[6:7], 0, v[134:135]
	global_load_dwordx4 v[134:137], v[152:153], off offset:48
	global_load_dwordx4 v[148:151], v[152:153], off offset:32
	global_load_dwordx4 v[158:161], v[152:153], off offset:16
	global_load_dwordx4 v[162:165], v[152:153], off
	s_lshl_b32 s17, s40, 6
	s_and_b32 s17, s17, 0xfffffc00
	s_andn2_b64 vcc, exec, s[2:3]
	s_waitcnt vmcnt(0)
	v_add_f32_e32 v148, v148, v149
	v_add_f32_e32 v150, v150, v151
	v_mov_b32_e32 v152, v163
	v_mov_b32_e32 v153, v164
	v_mov_b32_e32 v163, v165
	v_pk_add_f32 v[152:153], v[152:153], v[162:163]
	v_mov_b32_e32 v162, v159
	v_mov_b32_e32 v163, v160
	v_mov_b32_e32 v159, v161
	v_pk_add_f32 v[158:159], v[162:163], v[158:159]
	v_pk_add_f32 v[152:153], v[152:153], v[152:153] op_sel:[0,1] op_sel_hi:[1,0]
	v_pk_add_f32 v[158:159], v[158:159], v[158:159] op_sel:[0,1] op_sel_hi:[1,0]
	v_mov_b32_e32 v153, v134
	v_mov_b32_e32 v159, v135
	v_mov_b32_e32 v149, v136
	v_mov_b32_e32 v151, v137
	v_pk_add_f32 v[134:135], v[152:153], v[158:159]
	v_pk_add_f32 v[136:137], v[148:149], v[150:151]
	v_bitop3_b32 v159, s16, v241, v155 bitop3:0xc8
	v_pk_add_f32 v[134:135], v[134:135], v[136:137]
	s_lshl_b32 s16, s41, 8
	v_add_f32_e32 v134, v134, v135
	v_fmamk_f32 v134, v134, 0x3a800000, v235
	v_rsq_f32_e32 v157, v134
	v_mbcnt_hi_u32_b32 v135, -1, v233
	v_and_or_b32 v135, v135, 64, v146
	v_lshlrev_b32_e32 v158, 2, v135
	ds_bpermute_b32 v150, v158, v157
	ds_bpermute_b32 v151, v158, v157 offset:4
	ds_bpermute_b32 v136, v158, v157 offset:8
	ds_bpermute_b32 v137, v158, v157 offset:12
	ds_bpermute_b32 v152, v158, v157 offset:16
	ds_bpermute_b32 v153, v158, v157 offset:20
	ds_bpermute_b32 v148, v158, v157 offset:24
	ds_bpermute_b32 v149, v158, v157 offset:28
	s_add_i32 s17, s17, s16
	v_add_u32_e32 v134, s17, v147
	v_ashrrev_i32_e32 v135, 31, v134
	v_mov_b64_e32 v[160:161], 0
	v_lshl_add_u64 v[160:161], s[98:99], 0, v[160:161]
	s_waitcnt lgkmcnt(6)
	v_pk_mul_f32 v[126:127], v[126:127], v[150:151]
	s_waitcnt lgkmcnt(2)
	v_pk_mul_f32 v[162:163], v[122:123], v[152:153]
	v_pk_mul_f32 v[128:129], v[128:129], v[136:137]
	s_waitcnt lgkmcnt(0)
	v_pk_mul_f32 v[164:165], v[124:125], v[148:149]
	v_and_b32_e32 v122, 0xffffffe0, v155
	v_lshlrev_b32_e32 v122, 7, v122
	v_and_b32_e32 v123, 31, v155
	v_lshl_add_u32 v122, v123, 6, v122
	v_and_b32_e32 v123, 15, v147
	v_lshl_add_u32 v122, v123, 4, v122
	v_mov_b32_e32 v123, v0
	v_lshl_add_u64 v[124:125], v[160:161], 0, v[122:123]
	v_cvt_pk_bf16_f32 v126, v126, v127
	v_cvt_pk_bf16_f32 v127, v128, v129
	v_cvt_pk_bf16_f32 v128, v162, v163
	v_cvt_pk_bf16_f32 v129, v164, v165
	global_store_dwordx4 v[124:125], v[126:129], off
	v_pk_mul_f32 v[118:119], v[118:119], v[150:151]
	v_pk_mul_f32 v[120:121], v[120:121], v[136:137]
	v_or_b32_e32 v126, 16, v134
	v_ashrrev_i32_e32 v127, 31, v126
	v_mov_b64_e32 v[126:127], 0x100
	v_lshl_add_u64 v[126:127], s[98:99], 0, v[126:127]
	v_pk_mul_f32 v[128:129], v[114:115], v[152:153]
	v_pk_mul_f32 v[160:161], v[116:117], v[148:149]
	v_lshl_add_u64 v[114:115], v[126:127], 0, v[122:123]
	v_cvt_pk_bf16_f32 v116, v118, v119
	v_cvt_pk_bf16_f32 v117, v120, v121
	v_cvt_pk_bf16_f32 v118, v128, v129
	v_cvt_pk_bf16_f32 v119, v160, v161
	global_store_dwordx4 v[114:115], v[116:119], off
	v_pk_mul_f32 v[110:111], v[110:111], v[150:151]
	v_pk_mul_f32 v[112:113], v[112:113], v[136:137]
	v_or_b32_e32 v116, 32, v134
	v_ashrrev_i32_e32 v117, 31, v116
	v_mov_b64_e32 v[116:117], 0x800
	v_lshl_add_u64 v[116:117], s[98:99], 0, v[116:117]
	v_pk_mul_f32 v[118:119], v[106:107], v[152:153]
	v_pk_mul_f32 v[120:121], v[108:109], v[148:149]
	v_lshl_add_u64 v[106:107], v[116:117], 0, v[122:123]
	v_cvt_pk_bf16_f32 v108, v110, v111
	v_cvt_pk_bf16_f32 v109, v112, v113
	v_cvt_pk_bf16_f32 v110, v118, v119
	v_cvt_pk_bf16_f32 v111, v120, v121
	global_store_dwordx4 v[106:107], v[108:111], off
	v_pk_mul_f32 v[102:103], v[102:103], v[150:151]
	v_pk_mul_f32 v[104:105], v[104:105], v[136:137]
	v_or_b32_e32 v108, 48, v134
	v_ashrrev_i32_e32 v109, 31, v108
	v_mov_b64_e32 v[108:109], 0x900
	v_lshl_add_u64 v[108:109], s[98:99], 0, v[108:109]
	v_pk_mul_f32 v[110:111], v[98:99], v[152:153]
	v_pk_mul_f32 v[112:113], v[100:101], v[148:149]
	v_lshl_add_u64 v[98:99], v[108:109], 0, v[122:123]
	v_cvt_pk_bf16_f32 v100, v102, v103
	v_cvt_pk_bf16_f32 v101, v104, v105
	v_cvt_pk_bf16_f32 v102, v110, v111
	v_cvt_pk_bf16_f32 v103, v112, v113
	global_store_dwordx4 v[98:99], v[100:103], off
	v_pk_mul_f32 v[94:95], v[94:95], v[150:151]
	v_pk_mul_f32 v[96:97], v[96:97], v[136:137]
	v_add_u32_e32 v100, 0x80, v134
	v_ashrrev_i32_e32 v101, 31, v100
	v_mov_b64_e32 v[100:101], 0x100000
	v_lshl_add_u64 v[100:101], s[98:99], 0, v[100:101]
	v_pk_mul_f32 v[102:103], v[90:91], v[152:153]
	v_pk_mul_f32 v[104:105], v[92:93], v[148:149]
	v_lshl_add_u64 v[100:101], v[100:101], 0, v[122:123]
	v_cvt_pk_bf16_f32 v90, v94, v95
	v_cvt_pk_bf16_f32 v91, v96, v97
	v_cvt_pk_bf16_f32 v92, v102, v103
	v_cvt_pk_bf16_f32 v93, v104, v105
	global_store_dwordx4 v[100:101], v[90:93], off
	v_pk_mul_f32 v[86:87], v[86:87], v[150:151]
	v_pk_mul_f32 v[88:89], v[88:89], v[136:137]
	v_add_u32_e32 v90, 0x90, v134
	v_ashrrev_i32_e32 v91, 31, v90
	v_mov_b64_e32 v[90:91], 0x100100
	v_lshl_add_u64 v[90:91], s[98:99], 0, v[90:91]
	v_pk_mul_f32 v[92:93], v[82:83], v[152:153]
	v_pk_mul_f32 v[94:95], v[84:85], v[148:149]
	v_lshl_add_u64 v[90:91], v[90:91], 0, v[122:123]
	v_cvt_pk_bf16_f32 v82, v86, v87
	v_cvt_pk_bf16_f32 v83, v88, v89
	v_cvt_pk_bf16_f32 v84, v92, v93
	v_cvt_pk_bf16_f32 v85, v94, v95
	global_store_dwordx4 v[90:91], v[82:85], off
	v_pk_mul_f32 v[78:79], v[78:79], v[150:151]
	v_pk_mul_f32 v[80:81], v[80:81], v[136:137]
	v_add_u32_e32 v82, 0xa0, v134
	v_ashrrev_i32_e32 v83, 31, v82
	v_mov_b64_e32 v[82:83], 0x100800
	v_lshl_add_u64 v[82:83], s[98:99], 0, v[82:83]
	v_pk_mul_f32 v[84:85], v[74:75], v[152:153]
	v_pk_mul_f32 v[86:87], v[76:77], v[148:149]
	v_lshl_add_u64 v[82:83], v[82:83], 0, v[122:123]
	v_cvt_pk_bf16_f32 v74, v78, v79
	v_cvt_pk_bf16_f32 v75, v80, v81
	v_cvt_pk_bf16_f32 v76, v84, v85
	v_cvt_pk_bf16_f32 v77, v86, v87
	global_store_dwordx4 v[82:83], v[74:77], off
	v_pk_mul_f32 v[62:63], v[62:63], v[150:151]
	v_pk_mul_f32 v[64:65], v[64:65], v[136:137]
	v_add_u32_e32 v74, 0xb0, v134
	v_ashrrev_i32_e32 v75, 31, v74
	v_mov_b64_e32 v[74:75], 0x100900
	v_lshl_add_u64 v[74:75], s[98:99], 0, v[74:75]
	v_pk_mul_f32 v[76:77], v[58:59], v[152:153]
	v_pk_mul_f32 v[78:79], v[60:61], v[148:149]
	v_lshl_add_u64 v[74:75], v[74:75], 0, v[122:123]
	v_cvt_pk_bf16_f32 v58, v62, v63
	v_cvt_pk_bf16_f32 v59, v64, v65
	v_cvt_pk_bf16_f32 v60, v76, v77
	v_cvt_pk_bf16_f32 v61, v78, v79
	global_store_dwordx4 v[74:75], v[58:61], off
	ds_bpermute_b32 v62, v158, v157 offset:32
	ds_bpermute_b32 v63, v158, v157 offset:36
	v_or_b32_e32 v58, 60, v158
	ds_bpermute_b32 v64, v158, v157 offset:40
	ds_bpermute_b32 v65, v158, v157 offset:44
	ds_bpermute_b32 v76, v158, v157 offset:48
	ds_bpermute_b32 v77, v158, v157 offset:52
	ds_bpermute_b32 v78, v158, v157 offset:56
	ds_bpermute_b32 v79, v58, v157
	s_waitcnt lgkmcnt(6)
	v_pk_mul_f32 v[58:59], v[70:71], v[62:63]
	v_pk_mul_f32 v[54:55], v[54:55], v[62:63]
	s_waitcnt lgkmcnt(2)
	v_pk_mul_f32 v[60:61], v[66:67], v[76:77]
	v_pk_mul_f32 v[66:67], v[72:73], v[64:65]
	s_waitcnt lgkmcnt(0)
	v_pk_mul_f32 v[68:69], v[68:69], v[78:79]
	v_cvt_pk_bf16_f32 v58, v58, v59
	v_cvt_pk_bf16_f32 v59, v66, v67
	v_cvt_pk_bf16_f32 v60, v60, v61
	v_cvt_pk_bf16_f32 v61, v68, v69
	v_lshl_add_u64 v[124:125], v[124:125], 0, s[100:101]
	global_store_dwordx4 v[124:125], v[58:61], off
	v_pk_mul_f32 v[56:57], v[56:57], v[64:65]
	v_pk_mul_f32 v[46:47], v[46:47], v[62:63]
	v_pk_mul_f32 v[58:59], v[50:51], v[76:77]
	v_pk_mul_f32 v[60:61], v[52:53], v[78:79]
	v_cvt_pk_bf16_f32 v50, v54, v55
	v_cvt_pk_bf16_f32 v51, v56, v57
	v_cvt_pk_bf16_f32 v52, v58, v59
	v_cvt_pk_bf16_f32 v53, v60, v61
	v_lshl_add_u64 v[114:115], v[114:115], 0, s[100:101]
	global_store_dwordx4 v[114:115], v[50:53], off
	v_pk_mul_f32 v[48:49], v[48:49], v[64:65]
	v_pk_mul_f32 v[38:39], v[38:39], v[62:63]
	v_pk_mul_f32 v[50:51], v[42:43], v[76:77]
	v_pk_mul_f32 v[52:53], v[44:45], v[78:79]
	v_cvt_pk_bf16_f32 v42, v46, v47
	v_cvt_pk_bf16_f32 v43, v48, v49
	v_cvt_pk_bf16_f32 v44, v50, v51
	v_cvt_pk_bf16_f32 v45, v52, v53
	v_lshl_add_u64 v[106:107], v[106:107], 0, s[100:101]
	global_store_dwordx4 v[106:107], v[42:45], off
	v_pk_mul_f32 v[40:41], v[40:41], v[64:65]
	v_pk_mul_f32 v[30:31], v[30:31], v[62:63]
	v_pk_mul_f32 v[42:43], v[34:35], v[76:77]
	v_pk_mul_f32 v[44:45], v[36:37], v[78:79]
	v_cvt_pk_bf16_f32 v34, v38, v39
	v_cvt_pk_bf16_f32 v35, v40, v41
	v_cvt_pk_bf16_f32 v36, v42, v43
	v_cvt_pk_bf16_f32 v37, v44, v45
	v_lshl_add_u64 v[98:99], v[98:99], 0, s[100:101]
	global_store_dwordx4 v[98:99], v[34:37], off
	v_pk_mul_f32 v[32:33], v[32:33], v[64:65]
	v_pk_mul_f32 v[22:23], v[22:23], v[62:63]
	v_pk_mul_f32 v[34:35], v[26:27], v[76:77]
	v_pk_mul_f32 v[36:37], v[28:29], v[78:79]
	v_cvt_pk_bf16_f32 v26, v30, v31
	v_cvt_pk_bf16_f32 v27, v32, v33
	v_cvt_pk_bf16_f32 v28, v34, v35
	v_cvt_pk_bf16_f32 v29, v36, v37
	v_lshl_add_u64 v[100:101], v[100:101], 0, s[100:101]
	global_store_dwordx4 v[100:101], v[26:29], off
	v_pk_mul_f32 v[24:25], v[24:25], v[64:65]
	v_pk_mul_f32 v[14:15], v[14:15], v[62:63]
	v_pk_mul_f32 v[26:27], v[18:19], v[76:77]
	v_pk_mul_f32 v[28:29], v[20:21], v[78:79]
	v_cvt_pk_bf16_f32 v18, v22, v23
	v_cvt_pk_bf16_f32 v19, v24, v25
	v_cvt_pk_bf16_f32 v20, v26, v27
	v_cvt_pk_bf16_f32 v21, v28, v29
	v_lshl_add_u64 v[90:91], v[90:91], 0, s[100:101]
	global_store_dwordx4 v[90:91], v[18:21], off
	v_pk_mul_f32 v[16:17], v[16:17], v[64:65]
	v_pk_mul_f32 v[6:7], v[6:7], v[62:63]
	v_pk_mul_f32 v[18:19], v[10:11], v[76:77]
	v_pk_mul_f32 v[20:21], v[12:13], v[78:79]
	v_cvt_pk_bf16_f32 v10, v14, v15
	v_cvt_pk_bf16_f32 v11, v16, v17
	v_cvt_pk_bf16_f32 v12, v18, v19
	v_cvt_pk_bf16_f32 v13, v20, v21
	v_lshl_add_u64 v[82:83], v[82:83], 0, s[100:101]
	global_store_dwordx4 v[82:83], v[10:13], off
	v_pk_mul_f32 v[8:9], v[8:9], v[64:65]
	s_mov_b64 s[16:17], -1
	v_pk_mul_f32 v[10:11], v[2:3], v[76:77]
	v_pk_mul_f32 v[12:13], v[4:5], v[78:79]
	v_cvt_pk_bf16_f32 v2, v6, v7
	v_cvt_pk_bf16_f32 v3, v8, v9
	v_cvt_pk_bf16_f32 v4, v10, v11
	v_cvt_pk_bf16_f32 v5, v12, v13
	v_lshl_add_u64 v[74:75], v[74:75], 0, s[100:101]
	global_store_dwordx4 v[74:75], v[2:5], off
	s_cbranch_vccnz .LBB0_283
	s_andn2_b64 vcc, exec, s[4:5]
	s_cbranch_vccnz .LBB0_282
	s_barrier
	s_branch .LBB0_282
